# static s_setprio 1 for the lagging half (waves 4-7) across the differential-attention tile loops, reset after each loop
# baseline (speedup 1.0000x reference)
; #define LAS __attribute__((address_space(3)))
; #define GAS __attribute__((address_space(1)))
; template <int MODE, bool NOMAX = false> ...
;     ...
;     GAS bf16_t* Ow = AO + (size_t)(rowbase + q0 + wid * 32) * AOP + ocol;
;     LAS bf16_t* stg = (LAS bf16_t*)(shm + LOST) + wid * (DV * 32);
; #pragma unroll
;     for (int pass = 0; pass < NPASS; ++pass) {
;         const GAS bf16_t* Qw = QKV + (size_t)(rowbase + q0 + wid * 32) * PITCH + qcol + pass * 64;
;         const GAS bf16_t* ksrc = QKV + (size_t)(rowbase + lane) * PITCH + kcol + pass * 64 + wid * 8;
;         const GAS bf16_t* vsrc = QKV + (size_t)(rowbase + 16 * (wid & 3) + (lane >> 2)) * PITCH + vcol + (wid >> 2) * 32 + (lane & 3) * 8;
;         bf16x8 qr[4];
; #pragma unroll
;         for (int d0 = 0; d0 < 4; ++d0) qr[d0] = *(const GAS bf16x8*)(Qw + (size_t)r32 * PITCH + d0 * 16 + hi * 8);
;         float mhat = 0.f, l_reg = 0.f, carry = 0.f;
;         f32x16 o[ND];
; #pragma unroll
;         for (int d = 0; d < ND; ++d) o[d] = f32x16{};
;         u32x4 kreg, vreg0, vreg1 = u32x4{};
;         { const int kt = (MODE == 0) ? NT - 1 : it0; const size_t go = (size_t)kt * 64 * PITCH;
;           kreg = *(const GAS u32x4*)(ksrc + go); vreg0 = *(const GAS u32x4*)(vsrc + go); if (DV == 128) vreg1 = *(const GAS u32x4*)(vsrc + go + 64); }
;         u32x4 pw0 = u32x4{}, pw1 = u32x4{}, pw2 = u32x4{}, pw3 = u32x4{};
;         const bool lag = (wid >= 4); bool pend = false; int vs = 0, vsp = 0;
;         const int vbl = (int)(lds0 + LV) + ((lane >> 4) & 1) * 32 + (lane & 3) * 8 + (4 * hi + ((lane & 15) >> 2)) * 64;
;     ...
;         {   *(LAS u32x4*)(shm + LK + (it0 & 1) * 8192 + wid * 1024 + lane * 16) = kreg;
;             *(LAS u32x4*)(shm + LV + wid * 1024 + lane * 16) = vreg0;
;             if (DV == 128) *(LAS u32x4*)(shm + LV + 8192 + wid * 1024 + lane * 16) = vreg1;
;             const int kt1 = (MODE == 0) ? NT - 2 - it0 : it0 + 1; const size_t go = (size_t)kt1 * 64 * PITCH;
;             kreg = *(const GAS u32x4*)(ksrc + go); vreg0 = *(const GAS u32x4*)(vsrc + go); if (DV == 128) vreg1 = *(const GAS u32x4*)(vsrc + go + 64); }
.LBB0_1069:
	s_and_b64 vcc, exec, s[0:1]
	s_cbranch_vccz .LBB0_813
	v_mov_b32_e32 v1, v168
	s_or_b32 s0, s30, s21
	v_readfirstlane_b32 s15, v1
	s_ashr_i32 s14, s15, 6
	s_ashr_i32 s4, s15, 7
	s_lshl_b32 s1, s14, 5
	s_add_i32 s5, s4, s31
	s_ashr_i32 s2, s1, 31
	s_add_u32 s6, s1, s0
	s_addc_u32 s7, s2, 0
	s_mul_i32 s1, s6, 0x1800
	v_readlane_b32 s18, v246, 15
	v_and_b32_e32 v205, 63, v1
	s_mul_hi_i32 s0, s6, 0x1800
	v_readlane_b32 s19, v246, 16
	s_add_u32 s1, s18, s1
	s_addc_u32 s0, s19, s0
	s_lshl_b32 s70, s20, 1
	v_or_b32_e32 v2, s21, v205
	s_add_u32 s2, s1, s70
	v_mul_u32_u24_e32 v2, 0xc00, v2
	s_addc_u32 s3, s0, 0
	v_lshlrev_b32_e32 v6, 1, v2
	v_mov_b32_e32 v7, v0
	s_lshl_b32 s0, s14, 3
	v_lshl_add_u64 v[2:3], s[18:19], 0, v[6:7]
	s_ashr_i32 s1, s0, 31
	v_lshl_add_u64 v[2:3], v[2:3], 0, s[70:71]
	s_lshl_b64 s[0:1], s[0:1], 1
	v_lshl_add_u64 v[8:9], v[2:3], 0, s[0:1]
	s_lshl_b32 s8, s14, 4
	v_bfe_u32 v2, v1, 2, 4
	v_and_or_b32 v2, s8, 48, v2
	v_or_b32_e32 v2, s21, v2
	v_mul_u32_u24_e32 v2, 0xc00, v2
	s_ashr_i32 s8, s15, 3
	v_lshlrev_b32_e32 v10, 1, v2
	v_mov_b32_e32 v11, v0
	s_andn2_b32 s8, s8, 31
	v_lshl_add_u64 v[2:3], s[18:19], 0, v[10:11]
	s_ashr_i32 s9, s8, 31
	v_lshlrev_b32_e32 v4, 3, v1
	v_lshl_add_u64 v[2:3], v[2:3], 0, s[70:71]
	s_lshl_b64 s[10:11], s[8:9], 1
	v_and_b32_e32 v18, 24, v4
	v_lshl_add_u64 v[2:3], v[2:3], 0, s[10:11]
	v_lshlrev_b32_e32 v4, 1, v18
	v_mov_b32_e32 v5, v0
	v_lshl_add_u64 v[12:13], v[2:3], 0, v[4:5]
	s_mov_b64 s[8:9], 0x1400
	v_lshl_add_u64 v[14:15], v[12:13], 0, s[8:9]
	s_movk_i32 s8, 0x1000
	v_add_co_u32_e32 v16, vcc, s8, v12
	s_mov_b32 s12, 0x61000
	s_nop 0
	v_addc_co_u32_e32 v17, vcc, 0, v13, vcc
	v_add_co_u32_e32 v2, vcc, s8, v8
	v_and_b32_e32 v187, 31, v1
	s_nop 0
	v_addc_co_u32_e32 v3, vcc, 0, v9, vcc
	global_load_dwordx4 v[2:5], v[2:3], off
	s_nop 0
	global_load_dwordx4 v[120:123], v[16:17], off offset:1024
	global_load_dwordx4 v[124:127], v[14:15], off offset:128
	v_add_co_u32_e32 v12, vcc, s12, v12
	s_mov_b64 s[8:9], 0x1000
	v_mul_u32_u24_e32 v14, 0xc00, v187
	v_addc_co_u32_e32 v13, vcc, 0, v13, vcc
	v_bfe_u32 v19, v1, 5, 1
	s_waitcnt vmcnt(9)
	v_lshl_add_u64 v[158:159], v[8:9], 0, s[8:9]
	v_lshlrev_b32_e32 v14, 1, v14
	v_mov_b32_e32 v15, v0
	v_add_co_u32_e32 v8, vcc, s12, v8
	v_lshl_add_u64 v[14:15], s[2:3], 0, v[14:15]
	v_lshlrev_b32_e32 v16, 4, v19
	v_mov_b32_e32 v17, v0
	v_addc_co_u32_e32 v9, vcc, 0, v9, vcc
	s_waitcnt vmcnt(8)
	v_lshl_add_u64 v[160:161], v[14:15], 0, v[16:17]
	global_load_dwordx4 v[116:119], v[12:13], off offset:1024
	global_load_dwordx4 v[112:115], v[12:13], off offset:1152
	global_load_dwordx4 v[140:143], v[160:161], off offset:3072
	global_load_dwordx4 v[136:139], v[160:161], off offset:3104
	global_load_dwordx4 v[132:135], v[160:161], off offset:3136
	global_load_dwordx4 v[128:131], v[160:161], off offset:3168
	global_load_dwordx4 v[144:147], v[8:9], off
	s_cmp_gt_i32 s14, 3
	s_cselect_b64 s[8:9], -1, 0
	s_cmp_lt_i32 s14, 4
	s_movk_i32 s12, 0x4000
	s_cselect_b64 s[2:3], -1, 0
	s_addk_i32 s12, 0x100
	v_add_u32_e32 v12, s12, v18
	s_lshl_b32 s12, s14, 10
	s_add_i32 s13, s12, 0x100
	v_lshlrev_b32_e32 v203, 4, v205
	v_add_u32_e32 v204, s13, v203
	s_not_b32 s13, s35
	s_bfe_u32 s13, s13, 0x40005
	s_mul_i32 s13, s13, 0x180000
	v_readlane_b32 s16, v246, 49
	s_add_u32 s13, s13, 0xc0000
	s_lshl_b32 s16, s16, 8
	s_add_u32 s10, s10, s16
	v_lshlrev_b32_e32 v207, 2, v19
	v_bfe_u32 v9, v1, 2, 2
	s_addc_u32 s11, s11, 0
	v_bfe_u32 v186, v1, 4, 2
	v_lshlrev_b32_e32 v8, 1, v1
	v_and_b32_e32 v188, 15, v1
	v_or_b32_e32 v9, v207, v9
	v_and_b32_e32 v1, 3, v1
	s_add_u32 s0, s16, s0
	v_and_b32_e32 v8, 32, v8
	v_lshlrev_b32_e32 v9, 6, v9
	s_waitcnt vmcnt(9)
	ds_write_b128 v204, v[2:5]
	s_waitcnt vmcnt(8)
	ds_write_b128 v204, v[120:123] offset:16384
	s_waitcnt vmcnt(7)
	ds_write_b128 v204, v[124:127] offset:24576
	v_lshl_or_b32 v2, v1, 4, s10
	v_mov_b32_e32 v3, s11
	s_addc_u32 s1, 0, s1
	v_add3_u32 v189, v12, v8, v9
	v_lshlrev_b32_e32 v206, 10, v19
	v_lshlrev_b32_e32 v8, 4, v187
	v_lshl_add_u64 v[2:3], v[2:3], 0, v[10:11]
	v_lshl_add_u64 v[162:163], s[0:1], 0, v[6:7]
	v_readlane_b32 s0, v246, 45
	v_mov_b32_e32 v14, v0
	v_mov_b32_e32 v15, v0
	v_add3_u32 v202, s72, v206, v8
	v_lshl_add_u64 v[156:157], s[18:19], 0, v[2:3]
	v_readlane_b32 s1, v246, 46
	v_mov_b32_e32 v1, v0
	v_mov_b32_e32 v2, v0
	v_mov_b32_e32 v3, v0
	v_mov_b32_e32 v4, v0
	v_mov_b32_e32 v5, v0
	v_mov_b32_e32 v6, v0
	v_mov_b32_e32 v8, v0
	v_mov_b32_e32 v9, v0
	v_mov_b32_e32 v10, v0
	v_mov_b32_e32 v12, v0
	v_mov_b32_e32 v13, v0
	v_mov_b64_e32 v[78:79], v[14:15]
	v_mov_b64_e32 v[62:63], v[14:15]
	v_mov_b64_e32 v[30:31], v[14:15]
	s_waitcnt vmcnt(6)
	v_mov_b64_e32 v[154:155], v[118:119]
	s_waitcnt vmcnt(5)
	v_mov_b64_e32 v[150:151], v[114:115]
	v_mov_b64_e32 v[46:47], v[14:15]
	s_mov_b32 s17, 0
	v_lshl_add_u64 v[164:165], s[0:1], 0, v[162:163]
	s_mov_b64 s[0:1], 0
	v_mov_b32_e32 v208, 0
	s_mov_b64 s[10:11], 0
	v_mov_b32_e32 v80, 0
	v_mov_b32_e32 v81, 0
	v_mov_b32_e32 v82, 0
	v_mov_b32_e32 v83, 0
	v_mov_b32_e32 v84, 0
	v_mov_b32_e32 v85, 0
	v_mov_b32_e32 v86, 0
	v_mov_b32_e32 v87, 0
	v_mov_b32_e32 v88, 0
	v_mov_b32_e32 v89, 0
	v_mov_b32_e32 v90, 0
	v_mov_b32_e32 v91, 0
	v_mov_b32_e32 v92, 0
	v_mov_b32_e32 v93, 0
	v_mov_b32_e32 v94, 0
	v_mov_b32_e32 v95, 0
	v_mov_b64_e32 v[76:77], v[12:13]
	v_mov_b64_e32 v[74:75], v[10:11]
	v_mov_b64_e32 v[72:73], v[8:9]
	v_mov_b64_e32 v[70:71], v[6:7]
	v_mov_b64_e32 v[68:69], v[4:5]
	v_mov_b64_e32 v[66:67], v[2:3]
	v_mov_b64_e32 v[64:65], v[0:1]
	v_mov_b64_e32 v[60:61], v[12:13]
	v_mov_b64_e32 v[58:59], v[10:11]
	v_mov_b64_e32 v[56:57], v[8:9]
	v_mov_b64_e32 v[54:55], v[6:7]
	v_mov_b64_e32 v[52:53], v[4:5]
	v_mov_b64_e32 v[50:51], v[2:3]
	v_mov_b64_e32 v[48:49], v[0:1]
	v_mov_b64_e32 v[28:29], v[12:13]
	v_mov_b64_e32 v[26:27], v[10:11]
	v_mov_b64_e32 v[24:25], v[8:9]
	v_mov_b64_e32 v[22:23], v[6:7]
	v_mov_b64_e32 v[20:21], v[4:5]
	v_mov_b64_e32 v[18:19], v[2:3]
	v_mov_b64_e32 v[16:17], v[0:1]
	v_mov_b64_e32 v[152:153], v[116:117]
	v_mov_b64_e32 v[148:149], v[112:113]
	s_mov_b32 s19, 0
	s_mov_b32 s28, 0
	s_mov_b32 s16, 0
	v_mov_b64_e32 v[44:45], v[12:13]
	v_mov_b64_e32 v[42:43], v[10:11]
	v_mov_b64_e32 v[40:41], v[8:9]
	v_mov_b64_e32 v[38:39], v[6:7]
	v_mov_b64_e32 v[36:37], v[4:5]
	v_mov_b64_e32 v[34:35], v[2:3]
	v_mov_b64_e32 v[32:33], v[0:1]
	s_and_b64 vcc, exec, s[8:9]
	s_cbranch_vccz .Lnoprio_0
	s_setprio 1
; #define LAS __attribute__((address_space(3)))
; #define GAS __attribute__((address_space(1)))
; __device__ __forceinline__ void pv(f32x16* o, int vb, bf16x8 pa0, bf16x8 pa1, bf16x8 pa2, bf16x8 pa3) {
;     s16x4 lo[2][4], hi[2][4];
; #pragma unroll
;     for (int d0 = 0; d0 < 2; ++d0)
; #pragma unroll
;         for (int ks = 0; ks < 4; ++ks) {
;             asm volatile("ds_read_b64_tr_b16 %0,%1 offset:%c2" : "=&v"(lo[d0][ks]) : "v"(vb), "i"(d0 * 4096 + ks * 1024) : "memory");
;             asm volatile("ds_read_b64_tr_b16 %0,%1 offset:%c2" : "=&v"(hi[d0][ks]) : "v"(vb), "i"(d0 * 4096 + ks * 1024 + 512) : "memory"); }
;     asm volatile("s_waitcnt lgkmcnt(0)" ::: "memory"); __builtin_amdgcn_sched_barrier(0);
;     ...
;     o[0] = __builtin_amdgcn_mfma_f32_32x32x16_bf16(pa0, PK(0, 0), o[0], 0, 0, 0); o[1] = __builtin_amdgcn_mfma_f32_32x32x16_bf16(pa0, PK(1, 0), o[1], 0, 0, 0);
;     o[0] = __builtin_amdgcn_mfma_f32_32x32x16_bf16(pa1, PK(0, 1), o[0], 0, 0, 0); o[1] = __builtin_amdgcn_mfma_f32_32x32x16_bf16(pa1, PK(1, 1), o[1], 0, 0, 0);
;     o[0] = __builtin_amdgcn_mfma_f32_32x32x16_bf16(pa2, PK(0, 2), o[0], 0, 0, 0); o[1] = __builtin_amdgcn_mfma_f32_32x32x16_bf16(pa2, PK(1, 2), o[1], 0, 0, 0);
;     o[0] = __builtin_amdgcn_mfma_f32_32x32x16_bf16(pa3, PK(0, 3), o[0], 0, 0, 0); o[1] = __builtin_amdgcn_mfma_f32_32x32x16_bf16(pa3, PK(1, 3), o[1], 0, 0, 0);
; template <int MODE, bool NOMAX = false> ...
;     ...
;         for (int it = it0; it < NT; ++it) {
;             const int kt = (MODE == 0) ? NT - 1 - it : it, slot = it & 1;
;             const int vsn = (vs == 2) ? 0 : vs + 1;
;             __syncthreads();
;             if (it + 1 < NT) {
;                 *(LAS u32x4*)(shm + LK + (slot ^ 1) * 8192 + wid * 1024 + lane * 16) = kreg;
;                 *(LAS u32x4*)(shm + LV + vsn * 16384 + wid * 1024 + lane * 16) = vreg0;
;                 if (DV == 128) *(LAS u32x4*)(shm + LV + vsn * 16384 + 8192 + wid * 1024 + lane * 16) = vreg1; }
;             if (it + 2 < NT) { const int ktn = (MODE == 0) ? kt - 2 : kt + 2; const size_t go = (size_t)ktn * 64 * PITCH;
;                 kreg = *(const GAS u32x4*)(ksrc + go); vreg0 = *(const GAS u32x4*)(vsrc + go); if (DV == 128) vreg1 = *(const GAS u32x4*)(vsrc + go + 64); }
;             if (lag && pend) { ATT_PV(vbl + vsp * 16384); pend = false; }
.Lnoprio_0:
.LBB0_1071:
	s_add_i32 s18, s19, 1
	s_cmp_lg_u32 s19, 2
	s_mov_b32 s21, s19
	s_cselect_b32 s19, s18, 0
	s_and_b32 s27, s17, 0x2000
	s_xor_b32 s29, s27, 0x2000
	s_lshl_b32 s18, s19, 14
	v_add_u32_e32 v2, s29, v204
	v_lshl_add_u64 v[4:5], v[156:157], 0, s[10:11]
	s_waitcnt lgkmcnt(0)
	s_barrier
	v_add_u32_e32 v1, s18, v204
	s_waitcnt vmcnt(0)
	ds_write_b128 v2, v[144:147]
	ds_write_b128 v1, v[152:155] offset:16384
	ds_write_b128 v1, v[148:151] offset:24576
	v_lshl_add_u64 v[2:3], v[164:165], 0, s[10:11]
	v_add_co_u32_e32 v4, vcc, 0xc1000, v4
	s_and_b64 s[30:31], s[8:9], s[0:1]
	s_nop 0
	v_addc_co_u32_e32 v5, vcc, 0, v5, vcc
	global_load_dwordx4 v[144:147], v[2:3], off
	global_load_dwordx4 v[152:155], v[4:5], off offset:1024
	global_load_dwordx4 v[148:151], v[4:5], off offset:1152
	s_andn2_b64 vcc, exec, s[30:31]
	s_cbranch_vccnz .LBB0_1073
	v_lshl_add_u32 v1, s28, 14, v189
	ds_read_b64_tr_b16 v[2:3],v1 offset:0
	ds_read_b64_tr_b16 v[4:5],v1 offset:512
	ds_read_b64_tr_b16 v[6:7],v1 offset:1024
	ds_read_b64_tr_b16 v[8:9],v1 offset:1536
	ds_read_b64_tr_b16 v[10:11],v1 offset:2048
	ds_read_b64_tr_b16 v[12:13],v1 offset:2560
	ds_read_b64_tr_b16 v[96:97],v1 offset:3072
	ds_read_b64_tr_b16 v[98:99],v1 offset:3584
	ds_read_b64_tr_b16 v[100:101],v1 offset:4096
	ds_read_b64_tr_b16 v[102:103],v1 offset:4608
	ds_read_b64_tr_b16 v[104:105],v1 offset:5120
	ds_read_b64_tr_b16 v[106:107],v1 offset:5632
	ds_read_b64_tr_b16 v[108:109],v1 offset:6144
	ds_read_b64_tr_b16 v[110:111],v1 offset:6656
	ds_read_b64_tr_b16 v[176:177],v1 offset:7168
	ds_read_b64_tr_b16 v[178:179],v1 offset:7680
	s_waitcnt lgkmcnt(0)
	s_nop 0
	v_mfma_f32_32x32x16_bf16 v[32:47], v[80:83], v[2:5], v[32:47]
	v_add_u32_e32 v1, 0x2000, v1
	ds_read_b64_tr_b16 v[2:3],v1 offset:0
	ds_read_b64_tr_b16 v[4:5],v1 offset:512
	v_mfma_f32_32x32x16_bf16 v[16:31], v[80:83], v[100:103], v[16:31]
	v_mfma_f32_32x32x16_bf16 v[32:47], v[84:87], v[6:9], v[32:47]
	ds_read_b64_tr_b16 v[6:7],v1 offset:1024
	ds_read_b64_tr_b16 v[8:9],v1 offset:1536
	v_mfma_f32_32x32x16_bf16 v[16:31], v[84:87], v[104:107], v[16:31]
	v_mfma_f32_32x32x16_bf16 v[32:47], v[88:91], v[10:13], v[32:47]
	ds_read_b64_tr_b16 v[10:11],v1 offset:2048
	ds_read_b64_tr_b16 v[12:13],v1 offset:2560
	v_mfma_f32_32x32x16_bf16 v[16:31], v[88:91], v[108:111], v[16:31]
	v_mfma_f32_32x32x16_bf16 v[32:47], v[92:95], v[96:99], v[32:47]
	ds_read_b64_tr_b16 v[96:97],v1 offset:3072
	ds_read_b64_tr_b16 v[98:99],v1 offset:3584
	ds_read_b64_tr_b16 v[100:101],v1 offset:4096
	ds_read_b64_tr_b16 v[102:103],v1 offset:4608
	ds_read_b64_tr_b16 v[104:105],v1 offset:5120
	ds_read_b64_tr_b16 v[106:107],v1 offset:5632
	ds_read_b64_tr_b16 v[108:109],v1 offset:6144
	v_mfma_f32_32x32x16_bf16 v[16:31], v[92:95], v[176:179], v[16:31]
	ds_read_b64_tr_b16 v[110:111],v1 offset:6656
	ds_read_b64_tr_b16 v[176:177],v1 offset:7168
	ds_read_b64_tr_b16 v[178:179],v1 offset:7680
	s_waitcnt lgkmcnt(0)
	v_mfma_f32_32x32x16_bf16 v[48:63], v[80:83], v[2:5], v[48:63]
	s_mov_b64 s[0:1], 0
	v_mfma_f32_32x32x16_bf16 v[64:79], v[80:83], v[100:103], v[64:79]
	v_mfma_f32_32x32x16_bf16 v[48:63], v[84:87], v[6:9], v[48:63]
	v_mfma_f32_32x32x16_bf16 v[64:79], v[84:87], v[104:107], v[64:79]
	v_mfma_f32_32x32x16_bf16 v[48:63], v[88:91], v[10:13], v[48:63]
	v_mfma_f32_32x32x16_bf16 v[64:79], v[88:91], v[108:111], v[64:79]
	v_mfma_f32_32x32x16_bf16 v[48:63], v[92:95], v[96:99], v[48:63]
	v_mfma_f32_32x32x16_bf16 v[64:79], v[92:95], v[176:179], v[64:79]

; #define LAS __attribute__((address_space(3)))
; #define GAS __attribute__((address_space(1)))
; #define ATT_PV(VB_) do { pv(o, (VB_), __builtin_bit_cast(bf16x8, pw0), __builtin_bit_cast(bf16x8, pw1), __builtin_bit_cast(bf16x8, pw2), __builtin_bit_cast(bf16x8, pw3)); \
;             if (DV == 128) pv(o + 2, (VB_) + 8192, __builtin_bit_cast(bf16x8, pw0), __builtin_bit_cast(bf16x8, pw1), __builtin_bit_cast(bf16x8, pw2), __builtin_bit_cast(bf16x8, pw3)); } while (0)
; template <int MODE, bool NOMAX = false> ...
;     ...
;         for (int it = it0; it < NT; ++it) {
;             const int kt = (MODE == 0) ? NT - 1 - it : it, slot = it & 1;
;             const int vsn = (vs == 2) ? 0 : vs + 1;
;             __syncthreads();
;             if (it + 1 < NT) {
;                 *(LAS u32x4*)(shm + LK + (slot ^ 1) * 8192 + wid * 1024 + lane * 16) = kreg;
;                 *(LAS u32x4*)(shm + LV + vsn * 16384 + wid * 1024 + lane * 16) = vreg0;
;                 if (DV == 128) *(LAS u32x4*)(shm + LV + vsn * 16384 + 8192 + wid * 1024 + lane * 16) = vreg1; }
;             if (it + 2 < NT) { const int ktn = (MODE == 0) ? kt - 2 : kt + 2; const size_t go = (size_t)ktn * 64 * PITCH;
;                 kreg = *(const GAS u32x4*)(ksrc + go); vreg0 = *(const GAS u32x4*)(vsrc + go); if (DV == 128) vreg1 = *(const GAS u32x4*)(vsrc + go + 64); }
;             if (lag && pend) { ATT_PV(vbl + vsp * 16384); pend = false; }
;     ...
;         if (lag && pend) ATT_PV(vbl + vsp * 16384);
.LBB0_1080:
	s_setprio 0
	s_add_i32 s10, s18, 0x4000
	s_cmp_lg_u32 s19, 2
	s_cselect_b32 s17, s10, 0
	s_add_i32 s10, s17, 0x100
	s_add_i32 s10, s10, s12
	v_add_u32_e32 v1, s10, v203
	s_lshl_b32 s10, s16, 13
	s_and_b32 s19, s10, 0x2000
	s_xor_b32 s10, s19, 0x2000
	v_add_u32_e32 v166, s10, v204
	s_and_b64 s[10:11], s[8:9], s[0:1]
	s_andn2_b64 vcc, exec, s[10:11]
	s_waitcnt lgkmcnt(0)
	s_barrier
	s_waitcnt vmcnt(2)
	ds_write_b128 v166, v[144:147]
	s_waitcnt vmcnt(1)
	ds_write_b128 v1, v[152:155] offset:16384
	s_waitcnt vmcnt(0)
	ds_write_b128 v1, v[148:151] offset:24576
	s_cbranch_vccnz .LBB0_1082
	v_lshl_add_u32 v1, s21, 14, v189
	ds_read_b64_tr_b16 v[2:3],v1 offset:0
	ds_read_b64_tr_b16 v[4:5],v1 offset:512
	ds_read_b64_tr_b16 v[6:7],v1 offset:1024
	ds_read_b64_tr_b16 v[8:9],v1 offset:1536
	ds_read_b64_tr_b16 v[10:11],v1 offset:2048
	ds_read_b64_tr_b16 v[12:13],v1 offset:2560
	ds_read_b64_tr_b16 v[96:97],v1 offset:3072
	ds_read_b64_tr_b16 v[98:99],v1 offset:3584
	ds_read_b64_tr_b16 v[100:101],v1 offset:4096
	ds_read_b64_tr_b16 v[102:103],v1 offset:4608
	ds_read_b64_tr_b16 v[104:105],v1 offset:5120
	ds_read_b64_tr_b16 v[106:107],v1 offset:5632
	ds_read_b64_tr_b16 v[108:109],v1 offset:6144
	ds_read_b64_tr_b16 v[110:111],v1 offset:6656
	ds_read_b64_tr_b16 v[144:145],v1 offset:7168
	ds_read_b64_tr_b16 v[146:147],v1 offset:7680
	s_waitcnt lgkmcnt(0)
	s_nop 0
	v_mfma_f32_32x32x16_bf16 v[32:47], v[80:83], v[2:5], v[32:47]
	v_add_u32_e32 v1, 0x2000, v1
	ds_read_b64_tr_b16 v[2:3],v1 offset:0
	ds_read_b64_tr_b16 v[4:5],v1 offset:512
	v_mfma_f32_32x32x16_bf16 v[16:31], v[80:83], v[100:103], v[16:31]
	v_mfma_f32_32x32x16_bf16 v[32:47], v[84:87], v[6:9], v[32:47]
	ds_read_b64_tr_b16 v[6:7],v1 offset:1024
	ds_read_b64_tr_b16 v[8:9],v1 offset:1536
	v_mfma_f32_32x32x16_bf16 v[16:31], v[84:87], v[104:107], v[16:31]
	v_mfma_f32_32x32x16_bf16 v[32:47], v[88:91], v[10:13], v[32:47]
	ds_read_b64_tr_b16 v[10:11],v1 offset:2048
	ds_read_b64_tr_b16 v[12:13],v1 offset:2560
	v_mfma_f32_32x32x16_bf16 v[16:31], v[88:91], v[108:111], v[16:31]
	v_mfma_f32_32x32x16_bf16 v[32:47], v[92:95], v[96:99], v[32:47]
	ds_read_b64_tr_b16 v[96:97],v1 offset:3072
	ds_read_b64_tr_b16 v[98:99],v1 offset:3584
	ds_read_b64_tr_b16 v[100:101],v1 offset:4096
	ds_read_b64_tr_b16 v[102:103],v1 offset:4608
	ds_read_b64_tr_b16 v[104:105],v1 offset:5120
	ds_read_b64_tr_b16 v[106:107],v1 offset:5632
	ds_read_b64_tr_b16 v[108:109],v1 offset:6144
	v_mfma_f32_32x32x16_bf16 v[16:31], v[92:95], v[144:147], v[16:31]
	ds_read_b64_tr_b16 v[110:111],v1 offset:6656
	ds_read_b64_tr_b16 v[144:145],v1 offset:7168
	ds_read_b64_tr_b16 v[146:147],v1 offset:7680
	s_waitcnt lgkmcnt(0)
	v_mfma_f32_32x32x16_bf16 v[48:63], v[80:83], v[2:5], v[48:63]
	s_mov_b64 s[0:1], 0
	v_mfma_f32_32x32x16_bf16 v[64:79], v[80:83], v[100:103], v[64:79]
	v_mfma_f32_32x32x16_bf16 v[48:63], v[84:87], v[6:9], v[48:63]
	v_mfma_f32_32x32x16_bf16 v[64:79], v[84:87], v[104:107], v[64:79]
	v_mfma_f32_32x32x16_bf16 v[48:63], v[88:91], v[10:13], v[48:63]
	v_mfma_f32_32x32x16_bf16 v[64:79], v[88:91], v[108:111], v[64:79]
	v_mfma_f32_32x32x16_bf16 v[48:63], v[92:95], v[96:99], v[48:63]
	v_mfma_f32_32x32x16_bf16 v[64:79], v[92:95], v[144:147], v[64:79]

; #define LAS __attribute__((address_space(3)))
; __device__ __forceinline__ unsigned cvtpk(float lo, float hi) { f32x2_t v = {lo, hi}; bf16x2_t b = __builtin_convertvector(v, bf16x2_t); return __builtin_bit_cast(unsigned, b); }
; __device__ __forceinline__ int crow(int r, int hi) { return (r & 3) + 8 * (r >> 2) + 4 * hi; }
; __device__ __forceinline__ float partner32(float x, int hi) { auto rr = __builtin_amdgcn_permlane32_swap(__float_as_uint(x), __float_as_uint(x), false, false); return __uint_as_float(hi ? rr[0] : rr[1]); }
; template <int MODE, bool NOMAX = false> ...
;     ...
;         if (MODE != 0) {
;             const float lt = l_reg + partner32(l_reg, hi);
;             if (hi == 0) wsf[32 + r32] = lt;
;             asm volatile("s_waitcnt lgkmcnt(0)" ::: "memory");
; #pragma unroll
;             for (int g = 0; g < 4; ++g) { const f32x4 lv = *(const LAS f32x4*)(wsf + 32 + 8 * g + 4 * hi);
; #pragma unroll
;                 for (int i = 0; i < 4; ++i) { const float rl = __builtin_amdgcn_rcpf(lv[i]);
; #pragma unroll
;                     for (int d = 0; d < ND; ++d) o[d][4 * g + i] *= rl; } }
;         }
;         if (MODE == 2 && pass == 0) {
; #pragma unroll
;             for (int r = 0; r < 16; ++r) { const int orow = crow(r, hi);
; #pragma unroll
;                 for (int d = 0; d < ND; ++d) stg[orow * DV + d * 32 + r32] = (bf16_t)(cvtpk(o[d][r], 0.f) & 0xffffu); }
.LBB0_1091:
	s_and_b32 s0, s15, 0x3fffffc0
	s_lshl_b32 s0, s0, 2
	s_add_i32 s2, s0, 0x100
	s_add_i32 s2, s2, 0x10000
	v_mov_b32_e32 v2, v208
	v_mov_b32_e32 v1, v208
	v_cmp_gt_u32_e64 s[44:45], 32, v205
	v_lshl_add_u32 v165, v187, 2, s2
	v_permlane32_swap_b32_e32 v2, v1
	s_and_saveexec_b64 s[0:1], s[44:45]
	v_add_f32_e32 v1, v208, v1
	ds_write_b32 v165, v1 offset:128
	s_or_b64 exec, exec, s[0:1]
	v_lshl_add_u32 v155, v207, 2, s2
	s_waitcnt lgkmcnt(0)
	ds_read_b128 v[2:5], v155 offset:224
	ds_read_b128 v[10:13], v155 offset:192
	ds_read_b128 v[6:9], v155 offset:128
	ds_read_b128 v[80:83], v155 offset:160
	s_lshl_b32 s0, s14, 13
	s_waitcnt lgkmcnt(3)
	v_rcp_f32_e32 v5, v5
	s_add_i32 s14, s0, 0x100
	s_waitcnt lgkmcnt(1)
	v_rcp_f32_e32 v6, v6
	s_add_i32 s14, s14, 0x10800
	v_lshlrev_b32_e32 v1, 1, v187
	v_rcp_f32_e32 v7, v7
	v_mul_f32_e32 v14, v79, v5
	v_mul_f32_e32 v63, v63, v5
	v_mul_f32_e32 v31, v31, v5
	v_mul_f32_e32 v47, v47, v5
	v_mul_f32_e32 v5, v32, v6
	v_mul_f32_e32 v16, v16, v6
	v_add3_u32 v154, s14, v1, v206
	v_cvt_pk_bf16_f32 v1, v5, s0
	v_mul_f32_e32 v48, v48, v6
	ds_write_b16 v154, v1
	v_cvt_pk_bf16_f32 v1, v16, s0
	v_mul_f32_e32 v15, v64, v6
	ds_write_b16 v154, v1 offset:64
	v_cvt_pk_bf16_f32 v1, v48, s0
	v_rcp_f32_e32 v8, v8
	v_mul_f32_e32 v6, v33, v7
	ds_write_b16 v154, v1 offset:128
	v_cvt_pk_bf16_f32 v1, v15, s0
	v_mul_f32_e32 v17, v17, v7
	ds_write_b16 v154, v1 offset:192
	v_cvt_pk_bf16_f32 v1, v6, s0
	v_mul_f32_e32 v49, v49, v7
	ds_write_b16 v154, v1 offset:256
	v_cvt_pk_bf16_f32 v1, v17, s0
	v_mul_f32_e32 v64, v65, v7
	ds_write_b16 v154, v1 offset:320
	v_cvt_pk_bf16_f32 v1, v49, s0
	v_rcp_f32_e32 v9, v9
	v_mul_f32_e32 v7, v34, v8
	ds_write_b16 v154, v1 offset:384
	v_cvt_pk_bf16_f32 v1, v64, s0
	v_mul_f32_e32 v18, v18, v8
	ds_write_b16 v154, v1 offset:448
	v_cvt_pk_bf16_f32 v1, v7, s0
	v_mul_f32_e32 v50, v50, v8
	ds_write_b16 v154, v1 offset:512
	v_cvt_pk_bf16_f32 v1, v18, s0
	v_mul_f32_e32 v65, v66, v8
	ds_write_b16 v154, v1 offset:576
	v_cvt_pk_bf16_f32 v1, v50, s0
	s_waitcnt lgkmcnt(10)
	v_rcp_f32_e32 v66, v80
	v_mul_f32_e32 v8, v35, v9
	ds_write_b16 v154, v1 offset:640
	v_cvt_pk_bf16_f32 v1, v65, s0
	v_mul_f32_e32 v19, v19, v9
	ds_write_b16 v154, v1 offset:704
	v_cvt_pk_bf16_f32 v1, v8, s0
	v_mul_f32_e32 v51, v51, v9
	ds_write_b16 v154, v1 offset:768
	v_cvt_pk_bf16_f32 v1, v19, s0
	v_mul_f32_e32 v67, v67, v9
	ds_write_b16 v154, v1 offset:832
	v_cvt_pk_bf16_f32 v1, v51, s0
	v_rcp_f32_e32 v79, v81
	v_mul_f32_e32 v9, v36, v66
	ds_write_b16 v154, v1 offset:896
	v_cvt_pk_bf16_f32 v1, v67, s0
	v_mul_f32_e32 v20, v20, v66
	ds_write_b16 v154, v1 offset:960
	v_cvt_pk_bf16_f32 v1, v9, s0
	v_mul_f32_e32 v52, v52, v66
	ds_write_b16 v154, v1 offset:2048
	v_cvt_pk_bf16_f32 v1, v20, s0
	v_mul_f32_e32 v68, v68, v66
	ds_write_b16 v154, v1 offset:2112
	v_cvt_pk_bf16_f32 v1, v52, s0
	v_rcp_f32_e32 v80, v82
	v_mul_f32_e32 v32, v37, v79
	ds_write_b16 v154, v1 offset:2176
	v_cvt_pk_bf16_f32 v1, v68, s0
	v_mul_f32_e32 v21, v21, v79
	ds_write_b16 v154, v1 offset:2240
	v_cvt_pk_bf16_f32 v1, v32, s0
	v_mul_f32_e32 v53, v53, v79
	ds_write_b16 v154, v1 offset:2304
	v_cvt_pk_bf16_f32 v1, v21, s0
	v_mul_f32_e32 v69, v69, v79
	ds_write_b16 v154, v1 offset:2368
	v_cvt_pk_bf16_f32 v1, v53, s0
	v_rcp_f32_e32 v81, v83
	v_mul_f32_e32 v33, v38, v80
	ds_write_b16 v154, v1 offset:2432
	v_cvt_pk_bf16_f32 v1, v69, s0
	v_mul_f32_e32 v22, v22, v80
	ds_write_b16 v154, v1 offset:2496
	v_cvt_pk_bf16_f32 v1, v33, s0
	v_mul_f32_e32 v54, v54, v80
	ds_write_b16 v154, v1 offset:2560
	v_cvt_pk_bf16_f32 v1, v22, s0
	v_mul_f32_e32 v70, v70, v80
	ds_write_b16 v154, v1 offset:2624
	v_cvt_pk_bf16_f32 v1, v54, s0
	v_rcp_f32_e32 v10, v10
	v_rcp_f32_e32 v2, v2
	v_rcp_f32_e32 v3, v3
	v_rcp_f32_e32 v4, v4
	v_mul_f32_e32 v34, v39, v81
	ds_write_b16 v154, v1 offset:2688
	v_cvt_pk_bf16_f32 v1, v70, s0
	v_mul_f32_e32 v23, v23, v81
	ds_write_b16 v154, v1 offset:2752
	v_cvt_pk_bf16_f32 v1, v34, s0
	v_mul_f32_e32 v55, v55, v81
	ds_write_b16 v154, v1 offset:2816
	v_cvt_pk_bf16_f32 v1, v23, s0
	v_mul_f32_e32 v71, v71, v81
	ds_write_b16 v154, v1 offset:2880
	v_cvt_pk_bf16_f32 v1, v55, s0
	v_rcp_f32_e32 v11, v11
	v_mul_f32_e32 v72, v72, v10
	v_mul_f32_e32 v76, v76, v2
	v_mul_f32_e32 v77, v77, v3
	v_mul_f32_e32 v78, v78, v4
	v_mul_f32_e32 v56, v56, v10
	v_mul_f32_e32 v60, v60, v2
	v_mul_f32_e32 v61, v61, v3
	v_mul_f32_e32 v62, v62, v4
	v_mul_f32_e32 v24, v24, v10
	v_mul_f32_e32 v28, v28, v2
	v_mul_f32_e32 v29, v29, v3
	v_mul_f32_e32 v30, v30, v4
	v_mul_f32_e32 v10, v40, v10
	v_mul_f32_e32 v35, v44, v2
	v_mul_f32_e32 v36, v45, v3
	v_mul_f32_e32 v37, v46, v4
	global_load_dwordx4 v[128:131], v[160:161], off offset:3200
	global_load_dwordx4 v[2:5], v[158:159], off offset:128
	ds_write_b16 v154, v1 offset:2944
	v_cvt_pk_bf16_f32 v1, v71, s0
	ds_write_b16 v154, v1 offset:3008
	v_cvt_pk_bf16_f32 v1, v10, s0
	ds_write_b16 v154, v1 offset:4096
	v_cvt_pk_bf16_f32 v1, v24, s0
	ds_write_b16 v154, v1 offset:4160
	v_cvt_pk_bf16_f32 v1, v56, s0
	v_rcp_f32_e32 v12, v12
	v_mul_f32_e32 v73, v73, v11
	v_mul_f32_e32 v57, v57, v11
	v_mul_f32_e32 v25, v25, v11
	v_mul_f32_e32 v11, v41, v11
	ds_write_b16 v154, v1 offset:4224
	v_cvt_pk_bf16_f32 v1, v72, s0
	ds_write_b16 v154, v1 offset:4288
	v_cvt_pk_bf16_f32 v1, v11, s0
	ds_write_b16 v154, v1 offset:4352
	v_cvt_pk_bf16_f32 v1, v25, s0
	ds_write_b16 v154, v1 offset:4416
	v_cvt_pk_bf16_f32 v1, v57, s0
	v_mul_f32_e32 v74, v74, v12
	v_rcp_f32_e32 v13, v13
	v_mul_f32_e32 v58, v58, v12
	v_mul_f32_e32 v26, v26, v12
	v_mul_f32_e32 v12, v42, v12
	ds_write_b16 v154, v1 offset:4480
	v_cvt_pk_bf16_f32 v1, v73, s0
	ds_write_b16 v154, v1 offset:4544
	v_cvt_pk_bf16_f32 v1, v12, s0
; #define LAS __attribute__((address_space(3)))
; #define GAS __attribute__((address_space(1)))
; __device__ __forceinline__ unsigned cvtpk(float lo, float hi) { f32x2_t v = {lo, hi}; bf16x2_t b = __builtin_convertvector(v, bf16x2_t); return __builtin_bit_cast(unsigned, b); }
; __device__ __forceinline__ int crow(int r, int hi) { return (r & 3) + 8 * (r >> 2) + 4 * hi; }
; template <int MODE, bool NOMAX = false> ...
;     ...
;         const GAS bf16_t* Qw = QKV + (size_t)(rowbase + q0 + wid * 32) * PITCH + qcol + pass * 64;
;         const GAS bf16_t* ksrc = QKV + (size_t)(rowbase + lane) * PITCH + kcol + pass * 64 + wid * 8;
;         const GAS bf16_t* vsrc = QKV + (size_t)(rowbase + 16 * (wid & 3) + (lane >> 2)) * PITCH + vcol + (wid >> 2) * 32 + (lane & 3) * 8;
;         bf16x8 qr[4];
; #pragma unroll
;         for (int d0 = 0; d0 < 4; ++d0) qr[d0] = *(const GAS bf16x8*)(Qw + (size_t)r32 * PITCH + d0 * 16 + hi * 8);
;         float mhat = 0.f, l_reg = 0.f, carry = 0.f;
;         f32x16 o[ND];
; #pragma unroll
;         for (int d = 0; d < ND; ++d) o[d] = f32x16{};
;         u32x4 kreg, vreg0, vreg1 = u32x4{};
;         { const int kt = (MODE == 0) ? NT - 1 : it0; const size_t go = (size_t)kt * 64 * PITCH;
;           kreg = *(const GAS u32x4*)(ksrc + go); vreg0 = *(const GAS u32x4*)(vsrc + go); if (DV == 128) vreg1 = *(const GAS u32x4*)(vsrc + go + 64); }
;         u32x4 pw0 = u32x4{}, pw1 = u32x4{}, pw2 = u32x4{}, pw3 = u32x4{};
;         const bool lag = (wid >= 4); bool pend = false; int vs = 0, vsp = 0;
;         const int vbl = (int)(lds0 + LV) + ((lane >> 4) & 1) * 32 + (lane & 3) * 8 + (4 * hi + ((lane & 15) >> 2)) * 64;
;     ...
;         {   *(LAS u32x4*)(shm + LK + (it0 & 1) * 8192 + wid * 1024 + lane * 16) = kreg;
;             *(LAS u32x4*)(shm + LV + wid * 1024 + lane * 16) = vreg0;
;             if (DV == 128) *(LAS u32x4*)(shm + LV + 8192 + wid * 1024 + lane * 16) = vreg1;
;             const int kt1 = (MODE == 0) ? NT - 2 - it0 : it0 + 1; const size_t go = (size_t)kt1 * 64 * PITCH;
;             kreg = *(const GAS u32x4*)(ksrc + go); vreg0 = *(const GAS u32x4*)(vsrc + go); if (DV == 128) vreg1 = *(const GAS u32x4*)(vsrc + go + 64); }
;     ...
;             for (int r = 0; r < 16; ++r) { const int orow = crow(r, hi);
; #pragma unroll
;                 for (int d = 0; d < ND; ++d) stg[orow * DV + d * 32 + r32] = (bf16_t)(cvtpk(o[d][r], 0.f) & 0xffffu); }
	ds_write_b16 v154, v1 offset:4608
	v_cvt_pk_bf16_f32 v1, v26, s0
	ds_write_b16 v154, v1 offset:4672
	v_cvt_pk_bf16_f32 v1, v58, s0
	v_mul_f32_e32 v75, v75, v13
	v_mul_f32_e32 v59, v59, v13
	v_mul_f32_e32 v27, v27, v13
	v_mul_f32_e32 v13, v43, v13
	ds_write_b16 v154, v1 offset:4736
	v_cvt_pk_bf16_f32 v1, v74, s0
	ds_write_b16 v154, v1 offset:4800
	v_cvt_pk_bf16_f32 v1, v13, s0
	ds_write_b16 v154, v1 offset:4864
	v_cvt_pk_bf16_f32 v1, v27, s0
	ds_write_b16 v154, v1 offset:4928
	v_cvt_pk_bf16_f32 v1, v59, s0
	ds_write_b16 v154, v1 offset:4992
	v_cvt_pk_bf16_f32 v1, v75, s0
	ds_write_b16 v154, v1 offset:5056
	v_cvt_pk_bf16_f32 v1, v35, s0
	s_mov_b32 s0, 0x60000
	ds_write_b16 v154, v1 offset:6144
	v_add_co_u32_e32 v6, vcc, s0, v158
	global_load_dwordx4 v[140:143], v[160:161], off offset:3232
	global_load_dwordx4 v[136:139], v[160:161], off offset:3264
	global_load_dwordx4 v[132:135], v[160:161], off offset:3296
	v_addc_co_u32_e32 v7, vcc, 0, v159, vcc
	global_load_dwordx4 v[144:147], v[6:7], off offset:128
	v_cvt_pk_bf16_f32 v1, v28, s0
	ds_write_b16 v154, v1 offset:6208
	v_cvt_pk_bf16_f32 v1, v60, s0
	ds_write_b16 v154, v1 offset:6272
	v_cvt_pk_bf16_f32 v1, v76, s0
	ds_write_b16 v154, v1 offset:6336
	v_cvt_pk_bf16_f32 v1, v36, s0
	ds_write_b16 v154, v1 offset:6400
	v_cvt_pk_bf16_f32 v1, v29, s0
	ds_write_b16 v154, v1 offset:6464
	v_cvt_pk_bf16_f32 v1, v61, s0
	ds_write_b16 v154, v1 offset:6528
	v_cvt_pk_bf16_f32 v1, v77, s0
	ds_write_b16 v154, v1 offset:6592
	v_cvt_pk_bf16_f32 v1, v37, s0
	ds_write_b16 v154, v1 offset:6656
	v_cvt_pk_bf16_f32 v1, v30, s0
	ds_write_b16 v154, v1 offset:6720
	v_cvt_pk_bf16_f32 v1, v62, s0
	ds_write_b16 v154, v1 offset:6784
	v_cvt_pk_bf16_f32 v1, v78, s0
	ds_write_b16 v154, v1 offset:6848
	v_cvt_pk_bf16_f32 v1, v47, s0
	ds_write_b16 v154, v1 offset:6912
	v_cvt_pk_bf16_f32 v1, v31, s0
	ds_write_b16 v154, v1 offset:6976
	v_cvt_pk_bf16_f32 v1, v63, s0
	ds_write_b16 v154, v1 offset:7040
	v_cvt_pk_bf16_f32 v1, v14, s0
	v_readlane_b32 s0, v246, 47
	v_mov_b32_e32 v14, v0
	v_mov_b32_e32 v15, v0
	ds_write_b16 v154, v1 offset:7104
	s_waitcnt lgkmcnt(0)
	s_barrier
	s_waitcnt vmcnt(4)
	ds_write_b128 v204, v[2:5]
	ds_write_b128 v204, v[120:123] offset:16384
	ds_write_b128 v204, v[124:127] offset:24576
	v_readlane_b32 s1, v246, 48
	v_mov_b32_e32 v1, v0
	v_mov_b32_e32 v2, v0
	v_mov_b32_e32 v3, v0
	v_mov_b32_e32 v4, v0
	v_mov_b32_e32 v5, v0
	v_mov_b32_e32 v6, v0
	v_mov_b32_e32 v7, v0
	v_mov_b32_e32 v8, v0
	v_mov_b32_e32 v9, v0
	v_mov_b32_e32 v10, v0
	v_mov_b32_e32 v11, v0
	v_mov_b32_e32 v12, v0
	v_mov_b32_e32 v13, v0
	v_mov_b64_e32 v[78:79], v[14:15]
	v_mov_b64_e32 v[62:63], v[14:15]
	v_mov_b64_e32 v[46:47], v[14:15]
	v_mov_b64_e32 v[30:31], v[14:15]
	s_mov_b32 s16, 0
	v_lshl_add_u64 v[120:121], s[0:1], 0, v[162:163]
	s_mov_b64 s[0:1], 0
	v_mov_b32_e32 v158, 0
	s_mov_b64 s[2:3], 0
	v_mov_b32_e32 v80, 0
	v_mov_b32_e32 v81, 0
	v_mov_b32_e32 v82, 0
	v_mov_b32_e32 v83, 0
	v_mov_b32_e32 v84, 0
	v_mov_b32_e32 v85, 0
	v_mov_b32_e32 v86, 0
	v_mov_b32_e32 v87, 0
	v_mov_b32_e32 v88, 0
	v_mov_b32_e32 v89, 0
	v_mov_b32_e32 v90, 0
	v_mov_b32_e32 v91, 0
	v_mov_b32_e32 v92, 0
	v_mov_b32_e32 v93, 0
	v_mov_b32_e32 v94, 0
	v_mov_b32_e32 v95, 0
	v_mov_b64_e32 v[76:77], v[12:13]
	v_mov_b64_e32 v[74:75], v[10:11]
	v_mov_b64_e32 v[72:73], v[8:9]
	v_mov_b64_e32 v[70:71], v[6:7]
	v_mov_b64_e32 v[68:69], v[4:5]
	v_mov_b64_e32 v[66:67], v[2:3]
	v_mov_b64_e32 v[64:65], v[0:1]
	v_mov_b64_e32 v[60:61], v[12:13]
	v_mov_b64_e32 v[58:59], v[10:11]
	v_mov_b64_e32 v[56:57], v[8:9]
	v_mov_b64_e32 v[54:55], v[6:7]
	v_mov_b64_e32 v[52:53], v[4:5]
	v_mov_b64_e32 v[50:51], v[2:3]
	v_mov_b64_e32 v[48:49], v[0:1]
	v_mov_b64_e32 v[44:45], v[12:13]
	v_mov_b64_e32 v[42:43], v[10:11]
	v_mov_b64_e32 v[40:41], v[8:9]
	v_mov_b64_e32 v[38:39], v[6:7]
	v_mov_b64_e32 v[36:37], v[4:5]
	v_mov_b64_e32 v[34:35], v[2:3]
	v_mov_b64_e32 v[32:33], v[0:1]
	v_mov_b64_e32 v[28:29], v[12:13]
	v_mov_b64_e32 v[26:27], v[10:11]
	v_mov_b64_e32 v[24:25], v[8:9]
	v_mov_b64_e32 v[22:23], v[6:7]
	v_mov_b64_e32 v[20:21], v[4:5]
	v_mov_b64_e32 v[18:19], v[2:3]
	v_mov_b64_e32 v[16:17], v[0:1]
	s_mov_b32 s18, 0
	s_mov_b32 s27, 0
	s_mov_b32 s17, 0
	s_and_b64 vcc, exec, s[8:9]
	s_cbranch_vccz .Lnoprio_1
	s_setprio 1
; #define LAS __attribute__((address_space(3)))
; #define GAS __attribute__((address_space(1)))
; __device__ __forceinline__ void pv(f32x16* o, int vb, bf16x8 pa0, bf16x8 pa1, bf16x8 pa2, bf16x8 pa3) {
;     s16x4 lo[2][4], hi[2][4];
; #pragma unroll
;     for (int d0 = 0; d0 < 2; ++d0)
; #pragma unroll
;         for (int ks = 0; ks < 4; ++ks) {
;             asm volatile("ds_read_b64_tr_b16 %0,%1 offset:%c2" : "=&v"(lo[d0][ks]) : "v"(vb), "i"(d0 * 4096 + ks * 1024) : "memory");
;             asm volatile("ds_read_b64_tr_b16 %0,%1 offset:%c2" : "=&v"(hi[d0][ks]) : "v"(vb), "i"(d0 * 4096 + ks * 1024 + 512) : "memory"); }
;     asm volatile("s_waitcnt lgkmcnt(0)" ::: "memory"); __builtin_amdgcn_sched_barrier(0);
;     ...
;     o[0] = __builtin_amdgcn_mfma_f32_32x32x16_bf16(pa0, PK(0, 0), o[0], 0, 0, 0); o[1] = __builtin_amdgcn_mfma_f32_32x32x16_bf16(pa0, PK(1, 0), o[1], 0, 0, 0);
;     o[0] = __builtin_amdgcn_mfma_f32_32x32x16_bf16(pa1, PK(0, 1), o[0], 0, 0, 0); o[1] = __builtin_amdgcn_mfma_f32_32x32x16_bf16(pa1, PK(1, 1), o[1], 0, 0, 0);
;     o[0] = __builtin_amdgcn_mfma_f32_32x32x16_bf16(pa2, PK(0, 2), o[0], 0, 0, 0); o[1] = __builtin_amdgcn_mfma_f32_32x32x16_bf16(pa2, PK(1, 2), o[1], 0, 0, 0);
;     o[0] = __builtin_amdgcn_mfma_f32_32x32x16_bf16(pa3, PK(0, 3), o[0], 0, 0, 0); o[1] = __builtin_amdgcn_mfma_f32_32x32x16_bf16(pa3, PK(1, 3), o[1], 0, 0, 0);
; template <int MODE, bool NOMAX = false> ...
;     ...
;         for (int it = it0; it < NT; ++it) {
;             const int kt = (MODE == 0) ? NT - 1 - it : it, slot = it & 1;
;             const int vsn = (vs == 2) ? 0 : vs + 1;
;             __syncthreads();
;             if (it + 1 < NT) {
;                 *(LAS u32x4*)(shm + LK + (slot ^ 1) * 8192 + wid * 1024 + lane * 16) = kreg;
;                 *(LAS u32x4*)(shm + LV + vsn * 16384 + wid * 1024 + lane * 16) = vreg0;
;                 if (DV == 128) *(LAS u32x4*)(shm + LV + vsn * 16384 + 8192 + wid * 1024 + lane * 16) = vreg1; }
;             if (it + 2 < NT) { const int ktn = (MODE == 0) ? kt - 2 : kt + 2; const size_t go = (size_t)ktn * 64 * PITCH;
;                 kreg = *(const GAS u32x4*)(ksrc + go); vreg0 = *(const GAS u32x4*)(vsrc + go); if (DV == 128) vreg1 = *(const GAS u32x4*)(vsrc + go + 64); }
;             if (lag && pend) { ATT_PV(vbl + vsp * 16384); pend = false; }
.Lnoprio_1:
.LBB0_1094:
	s_add_i32 s15, s18, 1
	s_cmp_lg_u32 s18, 2
	s_mov_b32 s19, s18
	s_cselect_b32 s18, s15, 0
	s_and_b32 s21, s16, 0x2000
	s_xor_b32 s28, s21, 0x2000
	s_lshl_b32 s15, s18, 14
	v_add_u32_e32 v2, s28, v204
	v_lshl_add_u64 v[4:5], v[156:157], 0, s[2:3]
	s_waitcnt lgkmcnt(0)
	s_barrier
	v_add_u32_e32 v1, s15, v204
	s_waitcnt vmcnt(0)
	ds_write_b128 v2, v[144:147]
	ds_write_b128 v1, v[116:119] offset:16384
	ds_write_b128 v1, v[112:115] offset:24576
	v_lshl_add_u64 v[2:3], v[120:121], 0, s[2:3]
	v_add_co_u32_e32 v4, vcc, 0xc1000, v4
	s_and_b64 s[28:29], s[8:9], s[0:1]
	s_nop 0
	v_addc_co_u32_e32 v5, vcc, 0, v5, vcc
	global_load_dwordx4 v[144:147], v[2:3], off
	global_load_dwordx4 v[116:119], v[4:5], off offset:1024
	global_load_dwordx4 v[112:115], v[4:5], off offset:1152
	s_andn2_b64 vcc, exec, s[28:29]
	s_cbranch_vccnz .LBB0_1096
	v_lshl_add_u32 v1, s27, 14, v189
	ds_read_b64_tr_b16 v[2:3],v1 offset:0
	ds_read_b64_tr_b16 v[4:5],v1 offset:512
	ds_read_b64_tr_b16 v[6:7],v1 offset:1024
	ds_read_b64_tr_b16 v[8:9],v1 offset:1536
	ds_read_b64_tr_b16 v[10:11],v1 offset:2048
	ds_read_b64_tr_b16 v[12:13],v1 offset:2560
	ds_read_b64_tr_b16 v[96:97],v1 offset:3072
	ds_read_b64_tr_b16 v[98:99],v1 offset:3584
	ds_read_b64_tr_b16 v[100:101],v1 offset:4096
	ds_read_b64_tr_b16 v[102:103],v1 offset:4608
	ds_read_b64_tr_b16 v[104:105],v1 offset:5120
	ds_read_b64_tr_b16 v[106:107],v1 offset:5632
	ds_read_b64_tr_b16 v[108:109],v1 offset:6144
	ds_read_b64_tr_b16 v[110:111],v1 offset:6656
	ds_read_b64_tr_b16 v[122:123],v1 offset:7168
	ds_read_b64_tr_b16 v[124:125],v1 offset:7680
	s_waitcnt lgkmcnt(0)
	s_nop 0
	v_mfma_f32_32x32x16_bf16 v[16:31], v[80:83], v[2:5], v[16:31]
	v_add_u32_e32 v1, 0x2000, v1
	ds_read_b64_tr_b16 v[2:3],v1 offset:0
	ds_read_b64_tr_b16 v[4:5],v1 offset:512
	v_mfma_f32_32x32x16_bf16 v[32:47], v[80:83], v[100:103], v[32:47]
	v_mfma_f32_32x32x16_bf16 v[16:31], v[84:87], v[6:9], v[16:31]
	ds_read_b64_tr_b16 v[6:7],v1 offset:1024
	ds_read_b64_tr_b16 v[8:9],v1 offset:1536
	v_mfma_f32_32x32x16_bf16 v[32:47], v[84:87], v[104:107], v[32:47]
	v_mfma_f32_32x32x16_bf16 v[16:31], v[88:91], v[10:13], v[16:31]
	ds_read_b64_tr_b16 v[10:11],v1 offset:2048
	ds_read_b64_tr_b16 v[12:13],v1 offset:2560
	v_mfma_f32_32x32x16_bf16 v[32:47], v[88:91], v[108:111], v[32:47]
	v_mfma_f32_32x32x16_bf16 v[16:31], v[92:95], v[96:99], v[16:31]
	ds_read_b64_tr_b16 v[96:97],v1 offset:3072
	ds_read_b64_tr_b16 v[98:99],v1 offset:3584
	ds_read_b64_tr_b16 v[100:101],v1 offset:4096
	ds_read_b64_tr_b16 v[102:103],v1 offset:4608
	ds_read_b64_tr_b16 v[104:105],v1 offset:5120
	ds_read_b64_tr_b16 v[106:107],v1 offset:5632
	ds_read_b64_tr_b16 v[108:109],v1 offset:6144
	v_mfma_f32_32x32x16_bf16 v[32:47], v[92:95], v[122:125], v[32:47]
	ds_read_b64_tr_b16 v[110:111],v1 offset:6656
	ds_read_b64_tr_b16 v[122:123],v1 offset:7168
	ds_read_b64_tr_b16 v[124:125],v1 offset:7680
	s_waitcnt lgkmcnt(0)
	v_mfma_f32_32x32x16_bf16 v[48:63], v[80:83], v[2:5], v[48:63]
	s_mov_b64 s[0:1], 0
	v_mfma_f32_32x32x16_bf16 v[64:79], v[80:83], v[100:103], v[64:79]
	v_mfma_f32_32x32x16_bf16 v[48:63], v[84:87], v[6:9], v[48:63]
	v_mfma_f32_32x32x16_bf16 v[64:79], v[84:87], v[104:107], v[64:79]
	v_mfma_f32_32x32x16_bf16 v[48:63], v[88:91], v[10:13], v[48:63]
	v_mfma_f32_32x32x16_bf16 v[64:79], v[88:91], v[108:111], v[64:79]
	v_mfma_f32_32x32x16_bf16 v[48:63], v[92:95], v[96:99], v[48:63]
	v_mfma_f32_32x32x16_bf16 v[64:79], v[92:95], v[122:125], v[64:79]

; #define LAS __attribute__((address_space(3)))
; #define GAS __attribute__((address_space(1)))
; #define ATT_PV(VB_) do { pv(o, (VB_), __builtin_bit_cast(bf16x8, pw0), __builtin_bit_cast(bf16x8, pw1), __builtin_bit_cast(bf16x8, pw2), __builtin_bit_cast(bf16x8, pw3)); \
;             if (DV == 128) pv(o + 2, (VB_) + 8192, __builtin_bit_cast(bf16x8, pw0), __builtin_bit_cast(bf16x8, pw1), __builtin_bit_cast(bf16x8, pw2), __builtin_bit_cast(bf16x8, pw3)); } while (0)
; template <int MODE, bool NOMAX = false> ...
;     ...
;         for (int it = it0; it < NT; ++it) {
;             const int kt = (MODE == 0) ? NT - 1 - it : it, slot = it & 1;
;             const int vsn = (vs == 2) ? 0 : vs + 1;
;             __syncthreads();
;             if (it + 1 < NT) {
;                 *(LAS u32x4*)(shm + LK + (slot ^ 1) * 8192 + wid * 1024 + lane * 16) = kreg;
;                 *(LAS u32x4*)(shm + LV + vsn * 16384 + wid * 1024 + lane * 16) = vreg0;
;                 if (DV == 128) *(LAS u32x4*)(shm + LV + vsn * 16384 + 8192 + wid * 1024 + lane * 16) = vreg1; }
;             if (it + 2 < NT) { const int ktn = (MODE == 0) ? kt - 2 : kt + 2; const size_t go = (size_t)ktn * 64 * PITCH;
;                 kreg = *(const GAS u32x4*)(ksrc + go); vreg0 = *(const GAS u32x4*)(vsrc + go); if (DV == 128) vreg1 = *(const GAS u32x4*)(vsrc + go + 64); }
;             if (lag && pend) { ATT_PV(vbl + vsp * 16384); pend = false; }
;     ...
;         if (lag && pend) ATT_PV(vbl + vsp * 16384);
.LBB0_1103:
	s_setprio 0
	s_add_i32 s2, s15, 0x4000
	s_cmp_lg_u32 s18, 2
	s_cselect_b32 s2, s2, 0
	s_add_i32 s3, s2, 0x100
	s_add_i32 s3, s3, s12
	s_and_b64 s[12:13], s[8:9], s[0:1]
	v_add_u32_e32 v1, s3, v203
	s_andn2_b64 vcc, exec, s[12:13]
	s_waitcnt lgkmcnt(0)
	s_barrier
	s_waitcnt vmcnt(2)
	ds_write_b128 v166, v[144:147]
	s_waitcnt vmcnt(1)
	ds_write_b128 v1, v[116:119] offset:16384
	s_waitcnt vmcnt(0)
	ds_write_b128 v1, v[112:115] offset:24576
	s_cbranch_vccnz .LBB0_1105
	v_lshl_add_u32 v1, s19, 14, v189
	ds_read_b64_tr_b16 v[2:3],v1 offset:0
	ds_read_b64_tr_b16 v[4:5],v1 offset:512
	ds_read_b64_tr_b16 v[6:7],v1 offset:1024
	ds_read_b64_tr_b16 v[8:9],v1 offset:1536
	ds_read_b64_tr_b16 v[10:11],v1 offset:2048
	ds_read_b64_tr_b16 v[12:13],v1 offset:2560
	ds_read_b64_tr_b16 v[96:97],v1 offset:3072
	ds_read_b64_tr_b16 v[98:99],v1 offset:3584
	ds_read_b64_tr_b16 v[100:101],v1 offset:4096
	ds_read_b64_tr_b16 v[102:103],v1 offset:4608
	ds_read_b64_tr_b16 v[104:105],v1 offset:5120
	ds_read_b64_tr_b16 v[106:107],v1 offset:5632
	ds_read_b64_tr_b16 v[108:109],v1 offset:6144
	ds_read_b64_tr_b16 v[110:111],v1 offset:6656
	ds_read_b64_tr_b16 v[112:113],v1 offset:7168
	ds_read_b64_tr_b16 v[114:115],v1 offset:7680
	s_waitcnt lgkmcnt(0)
	s_nop 0
	v_mfma_f32_32x32x16_bf16 v[16:31], v[80:83], v[2:5], v[16:31]
	v_add_u32_e32 v1, 0x2000, v1
	ds_read_b64_tr_b16 v[2:3],v1 offset:0
	ds_read_b64_tr_b16 v[4:5],v1 offset:512
	v_mfma_f32_32x32x16_bf16 v[32:47], v[80:83], v[100:103], v[32:47]
	v_mfma_f32_32x32x16_bf16 v[16:31], v[84:87], v[6:9], v[16:31]
	ds_read_b64_tr_b16 v[6:7],v1 offset:1024
	ds_read_b64_tr_b16 v[8:9],v1 offset:1536
	v_mfma_f32_32x32x16_bf16 v[32:47], v[84:87], v[104:107], v[32:47]
	v_mfma_f32_32x32x16_bf16 v[16:31], v[88:91], v[10:13], v[16:31]
	ds_read_b64_tr_b16 v[10:11],v1 offset:2048
	ds_read_b64_tr_b16 v[12:13],v1 offset:2560
	v_mfma_f32_32x32x16_bf16 v[32:47], v[88:91], v[108:111], v[32:47]
	v_mfma_f32_32x32x16_bf16 v[16:31], v[92:95], v[96:99], v[16:31]
	ds_read_b64_tr_b16 v[96:97],v1 offset:3072
	ds_read_b64_tr_b16 v[98:99],v1 offset:3584
	ds_read_b64_tr_b16 v[100:101],v1 offset:4096
	ds_read_b64_tr_b16 v[102:103],v1 offset:4608
	ds_read_b64_tr_b16 v[104:105],v1 offset:5120
	ds_read_b64_tr_b16 v[106:107],v1 offset:5632
	ds_read_b64_tr_b16 v[108:109],v1 offset:6144
	v_mfma_f32_32x32x16_bf16 v[32:47], v[92:95], v[112:115], v[32:47]
	ds_read_b64_tr_b16 v[110:111],v1 offset:6656
	ds_read_b64_tr_b16 v[112:113],v1 offset:7168
	ds_read_b64_tr_b16 v[114:115],v1 offset:7680
	s_waitcnt lgkmcnt(0)
	v_mfma_f32_32x32x16_bf16 v[48:63], v[80:83], v[2:5], v[48:63]
	s_mov_b64 s[0:1], 0
	v_mfma_f32_32x32x16_bf16 v[64:79], v[80:83], v[100:103], v[64:79]
	v_mfma_f32_32x32x16_bf16 v[48:63], v[84:87], v[6:9], v[48:63]
	v_mfma_f32_32x32x16_bf16 v[64:79], v[84:87], v[104:107], v[64:79]
	v_mfma_f32_32x32x16_bf16 v[48:63], v[88:91], v[10:13], v[48:63]
	v_mfma_f32_32x32x16_bf16 v[64:79], v[88:91], v[108:111], v[64:79]
	v_mfma_f32_32x32x16_bf16 v[48:63], v[92:95], v[96:99], v[48:63]
	v_mfma_f32_32x32x16_bf16 v[64:79], v[92:95], v[112:115], v[64:79]
